# conv_branch processes its 8 items per thread last-first (rows written most recently by P1 first, cache residency); on top of the attention packed->scalar split
# speedup vs baseline: 1.0080x; 1.0080x over previous
.LBB0_251:
	v_and_b32_e32 v3, 31, v7
	v_mad_u32_u24 v2, s97, 7, v7
	v_lshlrev_b32_e32 v4, 5, v3
	v_lshlrev_b32_e32 v3, 4, v3
	global_load_dwordx4 v[212:215], v4, s[0:1]
	global_load_dwordx4 v[216:219], v4, s[0:1] offset:16
	global_load_dwordx4 v[220:223], v4, s[0:1] offset:1024
	global_load_dwordx4 v[224:227], v4, s[0:1] offset:1040
	global_load_dwordx4 v[228:231], v4, s[0:1] offset:2048
	global_load_dwordx4 v[232:235], v4, s[0:1] offset:2064
	global_load_dwordx4 v[236:239], v4, s[4:5]
	global_load_dwordx4 v[240:243], v4, s[4:5] offset:16
	v_lshrrev_b32_e32 v38, 5, v2
	v_and_b32_e32 v39, 0x1fff, v38
	v_cmp_gt_u32_e32 vcc, 2, v39
	v_mad_u32_u24 v40, v38, s75, v3
	v_lshl_add_u32 v7, v38, 11, v3
	v_subrev_u32_e32 v2, s97, v2
	v_cndmask_b32_e64 v41, v205, 0, vcc
	v_cndmask_b32_e64 v6, 1.0, 0, vcc
	v_cmp_eq_u32_e32 vcc, 0, v39
	v_add_u32_e32 v41, v40, v41
	global_load_dwordx4 v[44:47], v41, s[36:37]
	global_load_dwordx4 v[48:51], v41, s[36:37] offset:1024
	v_cndmask_b32_e64 v41, v206, 0, vcc
	v_cndmask_b32_e64 v8, 1.0, 0, vcc
	v_add_u32_e32 v41, v40, v41
	global_load_dwordx4 v[52:55], v41, s[36:37]
	global_load_dwordx4 v[56:59], v41, s[36:37] offset:1024
	global_load_dwordx4 v[60:63], v40, s[36:37]
	global_load_dwordx4 v[64:67], v40, s[36:37] offset:1024
	global_load_dwordx4 v[68:71], v40, s[36:37] offset:512
	global_load_dwordx4 v[72:75], v40, s[36:37] offset:1536
	v_lshrrev_b32_e32 v38, 5, v2
	v_and_b32_e32 v39, 0x1fff, v38
	v_cmp_gt_u32_e32 vcc, 2, v39
	v_mad_u32_u24 v40, v38, s75, v3
	v_lshl_add_u32 v11, v38, 11, v3
	v_subrev_u32_e32 v2, s97, v2
	v_cndmask_b32_e64 v41, v205, 0, vcc
	v_cndmask_b32_e64 v10, 1.0, 0, vcc
	v_cmp_eq_u32_e32 vcc, 0, v39
	v_add_u32_e32 v41, v40, v41
	global_load_dwordx4 v[76:79], v41, s[36:37]
	global_load_dwordx4 v[80:83], v41, s[36:37] offset:1024
	v_cndmask_b32_e64 v41, v206, 0, vcc
	v_cndmask_b32_e64 v12, 1.0, 0, vcc
	v_add_u32_e32 v41, v40, v41
	global_load_dwordx4 v[84:87], v41, s[36:37]
	global_load_dwordx4 v[88:91], v41, s[36:37] offset:1024
	global_load_dwordx4 v[92:95], v40, s[36:37]
	global_load_dwordx4 v[96:99], v40, s[36:37] offset:1024
	global_load_dwordx4 v[100:103], v40, s[36:37] offset:512
	global_load_dwordx4 v[104:107], v40, s[36:37] offset:1536
	v_lshrrev_b32_e32 v38, 5, v2
	v_and_b32_e32 v39, 0x1fff, v38
	v_cmp_gt_u32_e32 vcc, 2, v39
	v_mad_u32_u24 v40, v38, s75, v3
	v_lshl_add_u32 v15, v38, 11, v3
	v_subrev_u32_e32 v2, s97, v2
	v_cndmask_b32_e64 v41, v205, 0, vcc
	v_cndmask_b32_e64 v14, 1.0, 0, vcc
	v_cmp_eq_u32_e32 vcc, 0, v39
	v_add_u32_e32 v41, v40, v41
	global_load_dwordx4 v[108:111], v41, s[36:37]
	global_load_dwordx4 v[112:115], v41, s[36:37] offset:1024
	v_cndmask_b32_e64 v41, v206, 0, vcc
	v_cndmask_b32_e64 v16, 1.0, 0, vcc
	v_add_u32_e32 v41, v40, v41
	global_load_dwordx4 v[116:119], v41, s[36:37]
	global_load_dwordx4 v[120:123], v41, s[36:37] offset:1024
	global_load_dwordx4 v[124:127], v40, s[36:37]
	global_load_dwordx4 v[128:131], v40, s[36:37] offset:1024
	global_load_dwordx4 v[132:135], v40, s[36:37] offset:512
	global_load_dwordx4 v[136:139], v40, s[36:37] offset:1536
	v_lshrrev_b32_e32 v38, 5, v2
	v_and_b32_e32 v39, 0x1fff, v38
	v_cmp_gt_u32_e32 vcc, 2, v39
	v_mad_u32_u24 v40, v38, s75, v3
	v_lshl_add_u32 v19, v38, 11, v3
	v_subrev_u32_e32 v2, s97, v2
	v_cndmask_b32_e64 v41, v205, 0, vcc
	v_cndmask_b32_e64 v18, 1.0, 0, vcc
	v_cmp_eq_u32_e32 vcc, 0, v39
	v_add_u32_e32 v41, v40, v41
	global_load_dwordx4 v[162:165], v41, s[36:37]
	global_load_dwordx4 v[166:169], v41, s[36:37] offset:1024
	v_cndmask_b32_e64 v41, v206, 0, vcc
	v_cndmask_b32_e64 v20, 1.0, 0, vcc
	v_add_u32_e32 v41, v40, v41
	global_load_dwordx4 v[170:173], v41, s[36:37]
	global_load_dwordx4 v[174:177], v41, s[36:37] offset:1024
	global_load_dwordx4 v[178:181], v40, s[36:37]
	global_load_dwordx4 v[182:185], v40, s[36:37] offset:1024
	global_load_dwordx4 v[186:189], v40, s[36:37] offset:512
	global_load_dwordx4 v[190:193], v40, s[36:37] offset:1536
	s_waitcnt vmcnt(0)
	v_lshlrev_b32_e32 v22, 16, v44
	v_and_b32_e32 v23, 0xffff0000, v44
	v_lshlrev_b32_e32 v24, 16, v45
	v_and_b32_e32 v25, 0xffff0000, v45
	v_lshlrev_b32_e32 v26, 16, v46
	v_and_b32_e32 v27, 0xffff0000, v46
	v_lshlrev_b32_e32 v28, 16, v47
	v_and_b32_e32 v29, 0xffff0000, v47
	v_lshlrev_b32_e32 v30, 16, v48
	v_and_b32_e32 v31, 0xffff0000, v48
	v_lshlrev_b32_e32 v32, 16, v49
	v_and_b32_e32 v33, 0xffff0000, v49
	v_lshlrev_b32_e32 v34, 16, v50
	v_and_b32_e32 v35, 0xffff0000, v50
	v_lshlrev_b32_e32 v36, 16, v51
	v_and_b32_e32 v37, 0xffff0000, v51
	v_pk_mul_f32 v[22:23], v[22:23], v[30:31]
	v_pk_mul_f32 v[24:25], v[24:25], v[32:33]
	v_pk_mul_f32 v[26:27], v[26:27], v[34:35]
	v_pk_mul_f32 v[28:29], v[28:29], v[36:37]
	v_pk_mul_f32 v[244:245], v[212:213], v[6:7] op_sel_hi:[1,0]
	v_pk_mul_f32 v[246:247], v[214:215], v[6:7] op_sel_hi:[1,0]
	v_pk_mul_f32 v[248:249], v[216:217], v[6:7] op_sel_hi:[1,0]
	v_pk_mul_f32 v[4:5], v[218:219], v[6:7] op_sel_hi:[1,0]
	v_pk_fma_f32 v[140:141], v[244:245], v[22:23], 0 op_sel_hi:[1,1,0]
	v_pk_fma_f32 v[142:143], v[246:247], v[24:25], 0 op_sel_hi:[1,1,0]
	v_pk_fma_f32 v[144:145], v[248:249], v[26:27], 0 op_sel_hi:[1,1,0]
	v_pk_fma_f32 v[194:195], v[4:5], v[28:29], 0 op_sel_hi:[1,1,0]
	v_lshlrev_b32_e32 v22, 16, v52
	v_and_b32_e32 v23, 0xffff0000, v52
	v_lshlrev_b32_e32 v24, 16, v53
	v_and_b32_e32 v25, 0xffff0000, v53
	v_lshlrev_b32_e32 v26, 16, v54
	v_and_b32_e32 v27, 0xffff0000, v54
	v_lshlrev_b32_e32 v28, 16, v55
	v_and_b32_e32 v29, 0xffff0000, v55
	v_lshlrev_b32_e32 v30, 16, v56
	v_and_b32_e32 v31, 0xffff0000, v56
	v_lshlrev_b32_e32 v32, 16, v57
	v_and_b32_e32 v33, 0xffff0000, v57
	v_lshlrev_b32_e32 v34, 16, v58
	v_and_b32_e32 v35, 0xffff0000, v58
	v_lshlrev_b32_e32 v36, 16, v59
	v_and_b32_e32 v37, 0xffff0000, v59
	v_pk_mul_f32 v[22:23], v[22:23], v[30:31]
	v_pk_mul_f32 v[24:25], v[24:25], v[32:33]
	v_pk_mul_f32 v[26:27], v[26:27], v[34:35]
	v_pk_mul_f32 v[28:29], v[28:29], v[36:37]
	v_pk_mul_f32 v[244:245], v[220:221], v[8:9] op_sel_hi:[1,0]
	v_pk_mul_f32 v[246:247], v[222:223], v[8:9] op_sel_hi:[1,0]
	v_pk_mul_f32 v[248:249], v[224:225], v[8:9] op_sel_hi:[1,0]
	v_pk_mul_f32 v[4:5], v[226:227], v[8:9] op_sel_hi:[1,0]
	v_pk_fma_f32 v[140:141], v[244:245], v[22:23], v[140:141]
	v_pk_fma_f32 v[142:143], v[246:247], v[24:25], v[142:143]
	v_pk_fma_f32 v[144:145], v[248:249], v[26:27], v[144:145]
	v_pk_fma_f32 v[194:195], v[4:5], v[28:29], v[194:195]
	v_lshlrev_b32_e32 v22, 16, v60
	v_and_b32_e32 v23, 0xffff0000, v60
	v_lshlrev_b32_e32 v24, 16, v61
	v_and_b32_e32 v25, 0xffff0000, v61
	v_lshlrev_b32_e32 v26, 16, v62
	v_and_b32_e32 v27, 0xffff0000, v62
	v_lshlrev_b32_e32 v28, 16, v63
	v_and_b32_e32 v29, 0xffff0000, v63
	v_lshlrev_b32_e32 v30, 16, v64
	v_and_b32_e32 v31, 0xffff0000, v64
	v_lshlrev_b32_e32 v32, 16, v65
	v_and_b32_e32 v33, 0xffff0000, v65
	v_lshlrev_b32_e32 v34, 16, v66
	v_and_b32_e32 v35, 0xffff0000, v66
	v_lshlrev_b32_e32 v36, 16, v67
	v_and_b32_e32 v37, 0xffff0000, v67
	v_pk_mul_f32 v[22:23], v[22:23], v[30:31]
	v_pk_mul_f32 v[24:25], v[24:25], v[32:33]
	v_pk_mul_f32 v[26:27], v[26:27], v[34:35]
	v_pk_mul_f32 v[28:29], v[28:29], v[36:37]
	v_pk_fma_f32 v[140:141], v[228:229], v[22:23], v[140:141]
	v_pk_fma_f32 v[142:143], v[230:231], v[24:25], v[142:143]
	v_pk_fma_f32 v[144:145], v[232:233], v[26:27], v[144:145]
	v_pk_fma_f32 v[194:195], v[234:235], v[28:29], v[194:195]
	v_pk_add_f32 v[140:141], v[236:237], v[140:141]
	v_pk_add_f32 v[142:143], v[238:239], v[142:143]
	v_pk_add_f32 v[144:145], v[240:241], v[144:145]
	v_pk_add_f32 v[194:195], v[242:243], v[194:195]
	v_lshlrev_b32_e32 v30, 16, v68
	v_and_b32_e32 v31, 0xffff0000, v68
	v_lshlrev_b32_e32 v32, 16, v69
	v_and_b32_e32 v33, 0xffff0000, v69
	v_lshlrev_b32_e32 v34, 16, v70
	v_and_b32_e32 v35, 0xffff0000, v70
	v_lshlrev_b32_e32 v36, 16, v71
	v_and_b32_e32 v37, 0xffff0000, v71
	v_lshlrev_b32_e32 v22, 16, v72
	v_and_b32_e32 v23, 0xffff0000, v72
	v_lshlrev_b32_e32 v24, 16, v73
	v_and_b32_e32 v25, 0xffff0000, v73
	v_lshlrev_b32_e32 v26, 16, v74
	v_and_b32_e32 v27, 0xffff0000, v74
	v_lshlrev_b32_e32 v28, 16, v75
	v_and_b32_e32 v29, 0xffff0000, v75
	v_pk_mul_f32 v[140:141], v[140:141], v[30:31]
	v_pk_mul_f32 v[142:143], v[142:143], v[32:33]
	v_pk_mul_f32 v[144:145], v[144:145], v[34:35]
	v_pk_mul_f32 v[194:195], v[194:195], v[36:37]
	v_mul_f32_e32 v30, 0xbfb8aa3b, v22
	v_mul_f32_e32 v31, 0xbfb8aa3b, v23
	v_mul_f32_e32 v32, 0xbfb8aa3b, v24
	v_mul_f32_e32 v33, 0xbfb8aa3b, v25
	v_mul_f32_e32 v34, 0xbfb8aa3b, v26
	v_mul_f32_e32 v35, 0xbfb8aa3b, v27
	v_mul_f32_e32 v36, 0xbfb8aa3b, v28
	v_mul_f32_e32 v37, 0xbfb8aa3b, v29
	v_exp_f32_e32 v30, v30
	v_exp_f32_e32 v31, v31
	v_exp_f32_e32 v32, v32
	v_exp_f32_e32 v33, v33
	v_exp_f32_e32 v34, v34
	v_exp_f32_e32 v35, v35
	v_exp_f32_e32 v36, v36
	v_exp_f32_e32 v37, v37
	v_add_f32_e32 v30, 1.0, v30
	v_add_f32_e32 v31, 1.0, v31
	v_add_f32_e32 v32, 1.0, v32
	v_add_f32_e32 v33, 1.0, v33
	v_add_f32_e32 v34, 1.0, v34
	v_add_f32_e32 v35, 1.0, v35
	v_add_f32_e32 v36, 1.0, v36
	v_add_f32_e32 v37, 1.0, v37
	v_rcp_f32_e32 v30, v30
	v_rcp_f32_e32 v31, v31
	v_rcp_f32_e32 v32, v32
	v_rcp_f32_e32 v33, v33
	v_rcp_f32_e32 v34, v34
	v_rcp_f32_e32 v35, v35
	v_rcp_f32_e32 v36, v36
	v_rcp_f32_e32 v37, v37
	v_pk_mul_f32 v[30:31], v[30:31], v[22:23]
	v_pk_mul_f32 v[32:33], v[32:33], v[24:25]
	v_pk_mul_f32 v[34:35], v[34:35], v[26:27]
	v_pk_mul_f32 v[36:37], v[36:37], v[28:29]
	v_pk_mul_f32 v[140:141], v[140:141], v[30:31]
	v_pk_mul_f32 v[142:143], v[142:143], v[32:33]
	v_pk_mul_f32 v[144:145], v[144:145], v[34:35]
	v_pk_mul_f32 v[194:195], v[194:195], v[36:37]
	v_cvt_pk_bf16_f32 v44, v140, v141
	v_cvt_pk_bf16_f32 v45, v142, v143
	v_cvt_pk_bf16_f32 v46, v144, v145
	v_cvt_pk_bf16_f32 v47, v194, v195
	global_store_dwordx4 v7, v[44:47], s[34:35]
	v_lshlrev_b32_e32 v22, 16, v76
	v_and_b32_e32 v23, 0xffff0000, v76
	v_lshlrev_b32_e32 v24, 16, v77
	v_and_b32_e32 v25, 0xffff0000, v77
	v_lshlrev_b32_e32 v26, 16, v78
	v_and_b32_e32 v27, 0xffff0000, v78
	v_lshlrev_b32_e32 v28, 16, v79
	v_and_b32_e32 v29, 0xffff0000, v79
	v_lshlrev_b32_e32 v30, 16, v80
	v_and_b32_e32 v31, 0xffff0000, v80
	v_lshlrev_b32_e32 v32, 16, v81
	v_and_b32_e32 v33, 0xffff0000, v81
	v_lshlrev_b32_e32 v34, 16, v82
	v_and_b32_e32 v35, 0xffff0000, v82
	v_lshlrev_b32_e32 v36, 16, v83
	v_and_b32_e32 v37, 0xffff0000, v83
	v_pk_mul_f32 v[22:23], v[22:23], v[30:31]
	v_pk_mul_f32 v[24:25], v[24:25], v[32:33]
	v_pk_mul_f32 v[26:27], v[26:27], v[34:35]
	v_pk_mul_f32 v[28:29], v[28:29], v[36:37]
	v_pk_mul_f32 v[244:245], v[212:213], v[10:11] op_sel_hi:[1,0]
	v_pk_mul_f32 v[246:247], v[214:215], v[10:11] op_sel_hi:[1,0]
	v_pk_mul_f32 v[248:249], v[216:217], v[10:11] op_sel_hi:[1,0]
	v_pk_mul_f32 v[4:5], v[218:219], v[10:11] op_sel_hi:[1,0]
	v_pk_fma_f32 v[140:141], v[244:245], v[22:23], 0 op_sel_hi:[1,1,0]
	v_pk_fma_f32 v[142:143], v[246:247], v[24:25], 0 op_sel_hi:[1,1,0]
	v_pk_fma_f32 v[144:145], v[248:249], v[26:27], 0 op_sel_hi:[1,1,0]
	v_pk_fma_f32 v[194:195], v[4:5], v[28:29], 0 op_sel_hi:[1,1,0]
	v_lshlrev_b32_e32 v22, 16, v84
	v_and_b32_e32 v23, 0xffff0000, v84
	v_lshlrev_b32_e32 v24, 16, v85
	v_and_b32_e32 v25, 0xffff0000, v85
	v_lshlrev_b32_e32 v26, 16, v86
	v_and_b32_e32 v27, 0xffff0000, v86
	v_lshlrev_b32_e32 v28, 16, v87
	v_and_b32_e32 v29, 0xffff0000, v87
	v_lshlrev_b32_e32 v30, 16, v88
	v_and_b32_e32 v31, 0xffff0000, v88
	v_lshlrev_b32_e32 v32, 16, v89
	v_and_b32_e32 v33, 0xffff0000, v89
	v_lshlrev_b32_e32 v34, 16, v90
	v_and_b32_e32 v35, 0xffff0000, v90
	v_lshlrev_b32_e32 v36, 16, v91
	v_and_b32_e32 v37, 0xffff0000, v91
	v_pk_mul_f32 v[22:23], v[22:23], v[30:31]
	v_pk_mul_f32 v[24:25], v[24:25], v[32:33]
	v_pk_mul_f32 v[26:27], v[26:27], v[34:35]
	v_pk_mul_f32 v[28:29], v[28:29], v[36:37]
	v_pk_mul_f32 v[244:245], v[220:221], v[12:13] op_sel_hi:[1,0]
	v_pk_mul_f32 v[246:247], v[222:223], v[12:13] op_sel_hi:[1,0]
	v_pk_mul_f32 v[248:249], v[224:225], v[12:13] op_sel_hi:[1,0]
	v_pk_mul_f32 v[4:5], v[226:227], v[12:13] op_sel_hi:[1,0]
	v_pk_fma_f32 v[140:141], v[244:245], v[22:23], v[140:141]
	v_pk_fma_f32 v[142:143], v[246:247], v[24:25], v[142:143]
	v_pk_fma_f32 v[144:145], v[248:249], v[26:27], v[144:145]
	v_pk_fma_f32 v[194:195], v[4:5], v[28:29], v[194:195]
	v_lshlrev_b32_e32 v22, 16, v92
	v_and_b32_e32 v23, 0xffff0000, v92
	v_lshlrev_b32_e32 v24, 16, v93
	v_and_b32_e32 v25, 0xffff0000, v93
	v_lshlrev_b32_e32 v26, 16, v94
	v_and_b32_e32 v27, 0xffff0000, v94
	v_lshlrev_b32_e32 v28, 16, v95
	v_and_b32_e32 v29, 0xffff0000, v95
	v_lshlrev_b32_e32 v30, 16, v96
	v_and_b32_e32 v31, 0xffff0000, v96
	v_lshlrev_b32_e32 v32, 16, v97
	v_and_b32_e32 v33, 0xffff0000, v97
	v_lshlrev_b32_e32 v34, 16, v98
	v_and_b32_e32 v35, 0xffff0000, v98
	v_lshlrev_b32_e32 v36, 16, v99
	v_and_b32_e32 v37, 0xffff0000, v99
	v_pk_mul_f32 v[22:23], v[22:23], v[30:31]
	v_pk_mul_f32 v[24:25], v[24:25], v[32:33]
	v_pk_mul_f32 v[26:27], v[26:27], v[34:35]
	v_pk_mul_f32 v[28:29], v[28:29], v[36:37]
	v_pk_fma_f32 v[140:141], v[228:229], v[22:23], v[140:141]
	v_pk_fma_f32 v[142:143], v[230:231], v[24:25], v[142:143]
	v_pk_fma_f32 v[144:145], v[232:233], v[26:27], v[144:145]
	v_pk_fma_f32 v[194:195], v[234:235], v[28:29], v[194:195]
	v_pk_add_f32 v[140:141], v[236:237], v[140:141]
	v_pk_add_f32 v[142:143], v[238:239], v[142:143]
	v_pk_add_f32 v[144:145], v[240:241], v[144:145]
	v_pk_add_f32 v[194:195], v[242:243], v[194:195]
	v_lshlrev_b32_e32 v30, 16, v100
	v_and_b32_e32 v31, 0xffff0000, v100
	v_lshlrev_b32_e32 v32, 16, v101
	v_and_b32_e32 v33, 0xffff0000, v101
	v_lshlrev_b32_e32 v34, 16, v102
	v_and_b32_e32 v35, 0xffff0000, v102
	v_lshlrev_b32_e32 v36, 16, v103
	v_and_b32_e32 v37, 0xffff0000, v103
	v_lshlrev_b32_e32 v22, 16, v104
	v_and_b32_e32 v23, 0xffff0000, v104
	v_lshlrev_b32_e32 v24, 16, v105
	v_and_b32_e32 v25, 0xffff0000, v105
	v_lshlrev_b32_e32 v26, 16, v106
	v_and_b32_e32 v27, 0xffff0000, v106
	v_lshlrev_b32_e32 v28, 16, v107
	v_and_b32_e32 v29, 0xffff0000, v107
	v_pk_mul_f32 v[140:141], v[140:141], v[30:31]
	v_pk_mul_f32 v[142:143], v[142:143], v[32:33]
	v_pk_mul_f32 v[144:145], v[144:145], v[34:35]
	v_pk_mul_f32 v[194:195], v[194:195], v[36:37]
	v_mul_f32_e32 v30, 0xbfb8aa3b, v22
	v_mul_f32_e32 v31, 0xbfb8aa3b, v23
	v_mul_f32_e32 v32, 0xbfb8aa3b, v24
	v_mul_f32_e32 v33, 0xbfb8aa3b, v25
	v_mul_f32_e32 v34, 0xbfb8aa3b, v26
	v_mul_f32_e32 v35, 0xbfb8aa3b, v27
	v_mul_f32_e32 v36, 0xbfb8aa3b, v28
	v_mul_f32_e32 v37, 0xbfb8aa3b, v29
	v_exp_f32_e32 v30, v30
	v_exp_f32_e32 v31, v31
	v_exp_f32_e32 v32, v32
	v_exp_f32_e32 v33, v33
	v_exp_f32_e32 v34, v34
	v_exp_f32_e32 v35, v35
	v_exp_f32_e32 v36, v36
	v_exp_f32_e32 v37, v37
	v_add_f32_e32 v30, 1.0, v30
	v_add_f32_e32 v31, 1.0, v31
	v_add_f32_e32 v32, 1.0, v32
	v_add_f32_e32 v33, 1.0, v33
	v_add_f32_e32 v34, 1.0, v34
	v_add_f32_e32 v35, 1.0, v35
	v_add_f32_e32 v36, 1.0, v36
	v_add_f32_e32 v37, 1.0, v37
	v_rcp_f32_e32 v30, v30
	v_rcp_f32_e32 v31, v31
	v_rcp_f32_e32 v32, v32
	v_rcp_f32_e32 v33, v33
	v_rcp_f32_e32 v34, v34
	v_rcp_f32_e32 v35, v35
	v_rcp_f32_e32 v36, v36
	v_rcp_f32_e32 v37, v37
	v_pk_mul_f32 v[30:31], v[30:31], v[22:23]
	v_pk_mul_f32 v[32:33], v[32:33], v[24:25]
	v_pk_mul_f32 v[34:35], v[34:35], v[26:27]
	v_pk_mul_f32 v[36:37], v[36:37], v[28:29]
	v_pk_mul_f32 v[140:141], v[140:141], v[30:31]
	v_pk_mul_f32 v[142:143], v[142:143], v[32:33]
	v_pk_mul_f32 v[144:145], v[144:145], v[34:35]
	v_pk_mul_f32 v[194:195], v[194:195], v[36:37]
	v_cvt_pk_bf16_f32 v76, v140, v141
	v_cvt_pk_bf16_f32 v77, v142, v143
	v_cvt_pk_bf16_f32 v78, v144, v145
	v_cvt_pk_bf16_f32 v79, v194, v195
	global_store_dwordx4 v11, v[76:79], s[34:35]
	v_lshlrev_b32_e32 v22, 16, v108
	v_and_b32_e32 v23, 0xffff0000, v108
	v_lshlrev_b32_e32 v24, 16, v109
	v_and_b32_e32 v25, 0xffff0000, v109
	v_lshlrev_b32_e32 v26, 16, v110
	v_and_b32_e32 v27, 0xffff0000, v110
	v_lshlrev_b32_e32 v28, 16, v111
	v_and_b32_e32 v29, 0xffff0000, v111
	v_lshlrev_b32_e32 v30, 16, v112
	v_and_b32_e32 v31, 0xffff0000, v112
	v_lshlrev_b32_e32 v32, 16, v113
	v_and_b32_e32 v33, 0xffff0000, v113
	v_lshlrev_b32_e32 v34, 16, v114
	v_and_b32_e32 v35, 0xffff0000, v114
	v_lshlrev_b32_e32 v36, 16, v115
	v_and_b32_e32 v37, 0xffff0000, v115
	v_pk_mul_f32 v[22:23], v[22:23], v[30:31]
	v_pk_mul_f32 v[24:25], v[24:25], v[32:33]
	v_pk_mul_f32 v[26:27], v[26:27], v[34:35]
	v_pk_mul_f32 v[28:29], v[28:29], v[36:37]
	v_pk_mul_f32 v[244:245], v[212:213], v[14:15] op_sel_hi:[1,0]
	v_pk_mul_f32 v[246:247], v[214:215], v[14:15] op_sel_hi:[1,0]
	v_pk_mul_f32 v[248:249], v[216:217], v[14:15] op_sel_hi:[1,0]
	v_pk_mul_f32 v[4:5], v[218:219], v[14:15] op_sel_hi:[1,0]
	v_pk_fma_f32 v[140:141], v[244:245], v[22:23], 0 op_sel_hi:[1,1,0]
	v_pk_fma_f32 v[142:143], v[246:247], v[24:25], 0 op_sel_hi:[1,1,0]
	v_pk_fma_f32 v[144:145], v[248:249], v[26:27], 0 op_sel_hi:[1,1,0]
	v_pk_fma_f32 v[194:195], v[4:5], v[28:29], 0 op_sel_hi:[1,1,0]
	v_lshlrev_b32_e32 v22, 16, v116
	v_and_b32_e32 v23, 0xffff0000, v116
	v_lshlrev_b32_e32 v24, 16, v117
	v_and_b32_e32 v25, 0xffff0000, v117
	v_lshlrev_b32_e32 v26, 16, v118
	v_and_b32_e32 v27, 0xffff0000, v118
	v_lshlrev_b32_e32 v28, 16, v119
	v_and_b32_e32 v29, 0xffff0000, v119
	v_lshlrev_b32_e32 v30, 16, v120
	v_and_b32_e32 v31, 0xffff0000, v120
	v_lshlrev_b32_e32 v32, 16, v121
	v_and_b32_e32 v33, 0xffff0000, v121
	v_lshlrev_b32_e32 v34, 16, v122
	v_and_b32_e32 v35, 0xffff0000, v122
	v_lshlrev_b32_e32 v36, 16, v123
	v_and_b32_e32 v37, 0xffff0000, v123
	v_pk_mul_f32 v[22:23], v[22:23], v[30:31]
	v_pk_mul_f32 v[24:25], v[24:25], v[32:33]
	v_pk_mul_f32 v[26:27], v[26:27], v[34:35]
	v_pk_mul_f32 v[28:29], v[28:29], v[36:37]
	v_pk_mul_f32 v[244:245], v[220:221], v[16:17] op_sel_hi:[1,0]
	v_pk_mul_f32 v[246:247], v[222:223], v[16:17] op_sel_hi:[1,0]
	v_pk_mul_f32 v[248:249], v[224:225], v[16:17] op_sel_hi:[1,0]
	v_pk_mul_f32 v[4:5], v[226:227], v[16:17] op_sel_hi:[1,0]
	v_pk_fma_f32 v[140:141], v[244:245], v[22:23], v[140:141]
	v_pk_fma_f32 v[142:143], v[246:247], v[24:25], v[142:143]
	v_pk_fma_f32 v[144:145], v[248:249], v[26:27], v[144:145]
	v_pk_fma_f32 v[194:195], v[4:5], v[28:29], v[194:195]
	v_lshlrev_b32_e32 v22, 16, v124
	v_and_b32_e32 v23, 0xffff0000, v124
	v_lshlrev_b32_e32 v24, 16, v125
	v_and_b32_e32 v25, 0xffff0000, v125
	v_lshlrev_b32_e32 v26, 16, v126
	v_and_b32_e32 v27, 0xffff0000, v126
	v_lshlrev_b32_e32 v28, 16, v127
	v_and_b32_e32 v29, 0xffff0000, v127
	v_lshlrev_b32_e32 v30, 16, v128
	v_and_b32_e32 v31, 0xffff0000, v128
	v_lshlrev_b32_e32 v32, 16, v129
	v_and_b32_e32 v33, 0xffff0000, v129
	v_lshlrev_b32_e32 v34, 16, v130
	v_and_b32_e32 v35, 0xffff0000, v130
	v_lshlrev_b32_e32 v36, 16, v131
	v_and_b32_e32 v37, 0xffff0000, v131
	v_pk_mul_f32 v[22:23], v[22:23], v[30:31]
	v_pk_mul_f32 v[24:25], v[24:25], v[32:33]
	v_pk_mul_f32 v[26:27], v[26:27], v[34:35]
	v_pk_mul_f32 v[28:29], v[28:29], v[36:37]
	v_pk_fma_f32 v[140:141], v[228:229], v[22:23], v[140:141]
	v_pk_fma_f32 v[142:143], v[230:231], v[24:25], v[142:143]
	v_pk_fma_f32 v[144:145], v[232:233], v[26:27], v[144:145]
	v_pk_fma_f32 v[194:195], v[234:235], v[28:29], v[194:195]
	v_pk_add_f32 v[140:141], v[236:237], v[140:141]
	v_pk_add_f32 v[142:143], v[238:239], v[142:143]
	v_pk_add_f32 v[144:145], v[240:241], v[144:145]
	v_pk_add_f32 v[194:195], v[242:243], v[194:195]
	v_lshlrev_b32_e32 v30, 16, v132
	v_and_b32_e32 v31, 0xffff0000, v132
	v_lshlrev_b32_e32 v32, 16, v133
	v_and_b32_e32 v33, 0xffff0000, v133
	v_lshlrev_b32_e32 v34, 16, v134
	v_and_b32_e32 v35, 0xffff0000, v134
	v_lshlrev_b32_e32 v36, 16, v135
	v_and_b32_e32 v37, 0xffff0000, v135
	v_lshlrev_b32_e32 v22, 16, v136
	v_and_b32_e32 v23, 0xffff0000, v136
	v_lshlrev_b32_e32 v24, 16, v137
	v_and_b32_e32 v25, 0xffff0000, v137
	v_lshlrev_b32_e32 v26, 16, v138
	v_and_b32_e32 v27, 0xffff0000, v138
	v_lshlrev_b32_e32 v28, 16, v139
	v_and_b32_e32 v29, 0xffff0000, v139
	v_pk_mul_f32 v[140:141], v[140:141], v[30:31]
	v_pk_mul_f32 v[142:143], v[142:143], v[32:33]
	v_pk_mul_f32 v[144:145], v[144:145], v[34:35]
	v_pk_mul_f32 v[194:195], v[194:195], v[36:37]
	v_mul_f32_e32 v30, 0xbfb8aa3b, v22
	v_mul_f32_e32 v31, 0xbfb8aa3b, v23
	v_mul_f32_e32 v32, 0xbfb8aa3b, v24
	v_mul_f32_e32 v33, 0xbfb8aa3b, v25
	v_mul_f32_e32 v34, 0xbfb8aa3b, v26
	v_mul_f32_e32 v35, 0xbfb8aa3b, v27
	v_mul_f32_e32 v36, 0xbfb8aa3b, v28
	v_mul_f32_e32 v37, 0xbfb8aa3b, v29
	v_exp_f32_e32 v30, v30
	v_exp_f32_e32 v31, v31
	v_exp_f32_e32 v32, v32
	v_exp_f32_e32 v33, v33
	v_exp_f32_e32 v34, v34
	v_exp_f32_e32 v35, v35
	v_exp_f32_e32 v36, v36
	v_exp_f32_e32 v37, v37
	v_add_f32_e32 v30, 1.0, v30
	v_add_f32_e32 v31, 1.0, v31
	v_add_f32_e32 v32, 1.0, v32
	v_add_f32_e32 v33, 1.0, v33
	v_add_f32_e32 v34, 1.0, v34
	v_add_f32_e32 v35, 1.0, v35
	v_add_f32_e32 v36, 1.0, v36
	v_add_f32_e32 v37, 1.0, v37
	v_rcp_f32_e32 v30, v30
	v_rcp_f32_e32 v31, v31
	v_rcp_f32_e32 v32, v32
	v_rcp_f32_e32 v33, v33
	v_rcp_f32_e32 v34, v34
	v_rcp_f32_e32 v35, v35
	v_rcp_f32_e32 v36, v36
	v_rcp_f32_e32 v37, v37
	v_pk_mul_f32 v[30:31], v[30:31], v[22:23]
	v_pk_mul_f32 v[32:33], v[32:33], v[24:25]
	v_pk_mul_f32 v[34:35], v[34:35], v[26:27]
	v_pk_mul_f32 v[36:37], v[36:37], v[28:29]
	v_pk_mul_f32 v[140:141], v[140:141], v[30:31]
	v_pk_mul_f32 v[142:143], v[142:143], v[32:33]
	v_pk_mul_f32 v[144:145], v[144:145], v[34:35]
	v_pk_mul_f32 v[194:195], v[194:195], v[36:37]
	v_cvt_pk_bf16_f32 v108, v140, v141
	v_cvt_pk_bf16_f32 v109, v142, v143
	v_cvt_pk_bf16_f32 v110, v144, v145
	v_cvt_pk_bf16_f32 v111, v194, v195
	global_store_dwordx4 v15, v[108:111], s[34:35]
	v_lshlrev_b32_e32 v22, 16, v162
	v_and_b32_e32 v23, 0xffff0000, v162
	v_lshlrev_b32_e32 v24, 16, v163
	v_and_b32_e32 v25, 0xffff0000, v163
	v_lshlrev_b32_e32 v26, 16, v164
	v_and_b32_e32 v27, 0xffff0000, v164
	v_lshlrev_b32_e32 v28, 16, v165
	v_and_b32_e32 v29, 0xffff0000, v165
	v_lshlrev_b32_e32 v30, 16, v166
	v_and_b32_e32 v31, 0xffff0000, v166
	v_lshlrev_b32_e32 v32, 16, v167
	v_and_b32_e32 v33, 0xffff0000, v167
	v_lshlrev_b32_e32 v34, 16, v168
	v_and_b32_e32 v35, 0xffff0000, v168
	v_lshlrev_b32_e32 v36, 16, v169
	v_and_b32_e32 v37, 0xffff0000, v169
	v_pk_mul_f32 v[22:23], v[22:23], v[30:31]
	v_pk_mul_f32 v[24:25], v[24:25], v[32:33]
	v_pk_mul_f32 v[26:27], v[26:27], v[34:35]
	v_pk_mul_f32 v[28:29], v[28:29], v[36:37]
	v_pk_mul_f32 v[244:245], v[212:213], v[18:19] op_sel_hi:[1,0]
	v_pk_mul_f32 v[246:247], v[214:215], v[18:19] op_sel_hi:[1,0]
	v_pk_mul_f32 v[248:249], v[216:217], v[18:19] op_sel_hi:[1,0]
	v_pk_mul_f32 v[4:5], v[218:219], v[18:19] op_sel_hi:[1,0]
	v_pk_fma_f32 v[140:141], v[244:245], v[22:23], 0 op_sel_hi:[1,1,0]
	v_pk_fma_f32 v[142:143], v[246:247], v[24:25], 0 op_sel_hi:[1,1,0]
	v_pk_fma_f32 v[144:145], v[248:249], v[26:27], 0 op_sel_hi:[1,1,0]
	v_pk_fma_f32 v[194:195], v[4:5], v[28:29], 0 op_sel_hi:[1,1,0]
	v_lshlrev_b32_e32 v22, 16, v170
	v_and_b32_e32 v23, 0xffff0000, v170
	v_lshlrev_b32_e32 v24, 16, v171
	v_and_b32_e32 v25, 0xffff0000, v171
	v_lshlrev_b32_e32 v26, 16, v172
	v_and_b32_e32 v27, 0xffff0000, v172
	v_lshlrev_b32_e32 v28, 16, v173
	v_and_b32_e32 v29, 0xffff0000, v173
	v_lshlrev_b32_e32 v30, 16, v174
	v_and_b32_e32 v31, 0xffff0000, v174
	v_lshlrev_b32_e32 v32, 16, v175
	v_and_b32_e32 v33, 0xffff0000, v175
	v_lshlrev_b32_e32 v34, 16, v176
	v_and_b32_e32 v35, 0xffff0000, v176
	v_lshlrev_b32_e32 v36, 16, v177
	v_and_b32_e32 v37, 0xffff0000, v177
	v_pk_mul_f32 v[22:23], v[22:23], v[30:31]
	v_pk_mul_f32 v[24:25], v[24:25], v[32:33]
	v_pk_mul_f32 v[26:27], v[26:27], v[34:35]
	v_pk_mul_f32 v[28:29], v[28:29], v[36:37]
	v_pk_mul_f32 v[244:245], v[220:221], v[20:21] op_sel_hi:[1,0]
	v_pk_mul_f32 v[246:247], v[222:223], v[20:21] op_sel_hi:[1,0]
	v_pk_mul_f32 v[248:249], v[224:225], v[20:21] op_sel_hi:[1,0]
	v_pk_mul_f32 v[4:5], v[226:227], v[20:21] op_sel_hi:[1,0]
	v_pk_fma_f32 v[140:141], v[244:245], v[22:23], v[140:141]
	v_pk_fma_f32 v[142:143], v[246:247], v[24:25], v[142:143]
	v_pk_fma_f32 v[144:145], v[248:249], v[26:27], v[144:145]
	v_pk_fma_f32 v[194:195], v[4:5], v[28:29], v[194:195]
	v_lshlrev_b32_e32 v22, 16, v178
	v_and_b32_e32 v23, 0xffff0000, v178
	v_lshlrev_b32_e32 v24, 16, v179
	v_and_b32_e32 v25, 0xffff0000, v179
	v_lshlrev_b32_e32 v26, 16, v180
	v_and_b32_e32 v27, 0xffff0000, v180
	v_lshlrev_b32_e32 v28, 16, v181
	v_and_b32_e32 v29, 0xffff0000, v181
	v_lshlrev_b32_e32 v30, 16, v182
	v_and_b32_e32 v31, 0xffff0000, v182
	v_lshlrev_b32_e32 v32, 16, v183
	v_and_b32_e32 v33, 0xffff0000, v183
	v_lshlrev_b32_e32 v34, 16, v184
	v_and_b32_e32 v35, 0xffff0000, v184
	v_lshlrev_b32_e32 v36, 16, v185
	v_and_b32_e32 v37, 0xffff0000, v185
	v_pk_mul_f32 v[22:23], v[22:23], v[30:31]
	v_pk_mul_f32 v[24:25], v[24:25], v[32:33]
	v_pk_mul_f32 v[26:27], v[26:27], v[34:35]
	v_pk_mul_f32 v[28:29], v[28:29], v[36:37]
	v_pk_fma_f32 v[140:141], v[228:229], v[22:23], v[140:141]
	v_pk_fma_f32 v[142:143], v[230:231], v[24:25], v[142:143]
	v_pk_fma_f32 v[144:145], v[232:233], v[26:27], v[144:145]
	v_pk_fma_f32 v[194:195], v[234:235], v[28:29], v[194:195]
	v_pk_add_f32 v[140:141], v[236:237], v[140:141]
	v_pk_add_f32 v[142:143], v[238:239], v[142:143]
	v_pk_add_f32 v[144:145], v[240:241], v[144:145]
	v_pk_add_f32 v[194:195], v[242:243], v[194:195]
	v_lshlrev_b32_e32 v30, 16, v186
	v_and_b32_e32 v31, 0xffff0000, v186
	v_lshlrev_b32_e32 v32, 16, v187
	v_and_b32_e32 v33, 0xffff0000, v187
	v_lshlrev_b32_e32 v34, 16, v188
	v_and_b32_e32 v35, 0xffff0000, v188
	v_lshlrev_b32_e32 v36, 16, v189
	v_and_b32_e32 v37, 0xffff0000, v189
	v_lshlrev_b32_e32 v22, 16, v190
	v_and_b32_e32 v23, 0xffff0000, v190
	v_lshlrev_b32_e32 v24, 16, v191
	v_and_b32_e32 v25, 0xffff0000, v191
	v_lshlrev_b32_e32 v26, 16, v192
	v_and_b32_e32 v27, 0xffff0000, v192
	v_lshlrev_b32_e32 v28, 16, v193
	v_and_b32_e32 v29, 0xffff0000, v193
	v_pk_mul_f32 v[140:141], v[140:141], v[30:31]
	v_pk_mul_f32 v[142:143], v[142:143], v[32:33]
	v_pk_mul_f32 v[144:145], v[144:145], v[34:35]
	v_pk_mul_f32 v[194:195], v[194:195], v[36:37]
	v_mul_f32_e32 v30, 0xbfb8aa3b, v22
	v_mul_f32_e32 v31, 0xbfb8aa3b, v23
	v_mul_f32_e32 v32, 0xbfb8aa3b, v24
	v_mul_f32_e32 v33, 0xbfb8aa3b, v25
	v_mul_f32_e32 v34, 0xbfb8aa3b, v26
	v_mul_f32_e32 v35, 0xbfb8aa3b, v27
	v_mul_f32_e32 v36, 0xbfb8aa3b, v28
	v_mul_f32_e32 v37, 0xbfb8aa3b, v29
	v_exp_f32_e32 v30, v30
	v_exp_f32_e32 v31, v31
	v_exp_f32_e32 v32, v32
	v_exp_f32_e32 v33, v33
	v_exp_f32_e32 v34, v34
	v_exp_f32_e32 v35, v35
	v_exp_f32_e32 v36, v36
	v_exp_f32_e32 v37, v37
	v_add_f32_e32 v30, 1.0, v30
	v_add_f32_e32 v31, 1.0, v31
	v_add_f32_e32 v32, 1.0, v32
	v_add_f32_e32 v33, 1.0, v33
	v_add_f32_e32 v34, 1.0, v34
	v_add_f32_e32 v35, 1.0, v35
	v_add_f32_e32 v36, 1.0, v36
	v_add_f32_e32 v37, 1.0, v37
	v_rcp_f32_e32 v30, v30
	v_rcp_f32_e32 v31, v31
	v_rcp_f32_e32 v32, v32
	v_rcp_f32_e32 v33, v33
	v_rcp_f32_e32 v34, v34
	v_rcp_f32_e32 v35, v35
	v_rcp_f32_e32 v36, v36
	v_rcp_f32_e32 v37, v37
	v_pk_mul_f32 v[30:31], v[30:31], v[22:23]
	v_pk_mul_f32 v[32:33], v[32:33], v[24:25]
	v_pk_mul_f32 v[34:35], v[34:35], v[26:27]
	v_pk_mul_f32 v[36:37], v[36:37], v[28:29]
	v_pk_mul_f32 v[140:141], v[140:141], v[30:31]
	v_pk_mul_f32 v[142:143], v[142:143], v[32:33]
	v_pk_mul_f32 v[144:145], v[144:145], v[34:35]
	v_pk_mul_f32 v[194:195], v[194:195], v[36:37]
	v_cvt_pk_bf16_f32 v162, v140, v141
	v_cvt_pk_bf16_f32 v163, v142, v143
	v_cvt_pk_bf16_f32 v164, v144, v145
	v_cvt_pk_bf16_f32 v165, v194, v195
	global_store_dwordx4 v19, v[162:165], s[34:35]
	s_waitcnt vmcnt(0)
	v_lshrrev_b32_e32 v38, 5, v2
	v_and_b32_e32 v39, 0x1fff, v38
	v_cmp_gt_u32_e32 vcc, 2, v39
	v_mad_u32_u24 v40, v38, s75, v3
	v_lshl_add_u32 v42, v38, 11, v3
	v_subrev_u32_e32 v2, s97, v2
	v_cndmask_b32_e64 v41, v205, 0, vcc
	v_cndmask_b32_e64 v6, 1.0, 0, vcc
	v_cmp_eq_u32_e32 vcc, 0, v39
	v_add_u32_e32 v41, v40, v41
	global_load_dwordx4 v[44:47], v41, s[36:37]
	global_load_dwordx4 v[48:51], v41, s[36:37] offset:1024
	v_cndmask_b32_e64 v41, v206, 0, vcc
	v_cndmask_b32_e64 v8, 1.0, 0, vcc
	v_add_u32_e32 v41, v40, v41
	global_load_dwordx4 v[52:55], v41, s[36:37]
	global_load_dwordx4 v[56:59], v41, s[36:37] offset:1024
	global_load_dwordx4 v[60:63], v40, s[36:37]
	global_load_dwordx4 v[64:67], v40, s[36:37] offset:1024
	global_load_dwordx4 v[68:71], v40, s[36:37] offset:512
	global_load_dwordx4 v[72:75], v40, s[36:37] offset:1536
	v_lshrrev_b32_e32 v38, 5, v2
	v_and_b32_e32 v39, 0x1fff, v38
	v_cmp_gt_u32_e32 vcc, 2, v39
	v_mad_u32_u24 v40, v38, s75, v3
	v_lshl_add_u32 v9, v38, 11, v3
	v_subrev_u32_e32 v2, s97, v2
	v_cndmask_b32_e64 v41, v205, 0, vcc
	v_cndmask_b32_e64 v10, 1.0, 0, vcc
	v_cmp_eq_u32_e32 vcc, 0, v39
	v_add_u32_e32 v41, v40, v41
	global_load_dwordx4 v[76:79], v41, s[36:37]
	global_load_dwordx4 v[80:83], v41, s[36:37] offset:1024
	v_cndmask_b32_e64 v41, v206, 0, vcc
	v_cndmask_b32_e64 v12, 1.0, 0, vcc
	v_add_u32_e32 v41, v40, v41
	global_load_dwordx4 v[84:87], v41, s[36:37]
	global_load_dwordx4 v[88:91], v41, s[36:37] offset:1024
	global_load_dwordx4 v[92:95], v40, s[36:37]
	global_load_dwordx4 v[96:99], v40, s[36:37] offset:1024
	global_load_dwordx4 v[100:103], v40, s[36:37] offset:512
	global_load_dwordx4 v[104:107], v40, s[36:37] offset:1536
	v_lshrrev_b32_e32 v38, 5, v2
	v_and_b32_e32 v39, 0x1fff, v38
	v_cmp_gt_u32_e32 vcc, 2, v39
	v_mad_u32_u24 v40, v38, s75, v3
	v_lshl_add_u32 v13, v38, 11, v3
	v_subrev_u32_e32 v2, s97, v2
	v_cndmask_b32_e64 v41, v205, 0, vcc
	v_cndmask_b32_e64 v14, 1.0, 0, vcc
	v_cmp_eq_u32_e32 vcc, 0, v39
	v_add_u32_e32 v41, v40, v41
	global_load_dwordx4 v[108:111], v41, s[36:37]
	global_load_dwordx4 v[112:115], v41, s[36:37] offset:1024
	v_cndmask_b32_e64 v41, v206, 0, vcc
	v_cndmask_b32_e64 v16, 1.0, 0, vcc
	v_add_u32_e32 v41, v40, v41
	global_load_dwordx4 v[116:119], v41, s[36:37]
	global_load_dwordx4 v[120:123], v41, s[36:37] offset:1024
	global_load_dwordx4 v[124:127], v40, s[36:37]
	global_load_dwordx4 v[128:131], v40, s[36:37] offset:1024
	global_load_dwordx4 v[132:135], v40, s[36:37] offset:512
	global_load_dwordx4 v[136:139], v40, s[36:37] offset:1536
	v_lshrrev_b32_e32 v38, 5, v2
	v_and_b32_e32 v39, 0x1fff, v38
	v_cmp_gt_u32_e32 vcc, 2, v39
	v_mad_u32_u24 v40, v38, s75, v3
	v_lshl_add_u32 v17, v38, 11, v3
	v_subrev_u32_e32 v2, s97, v2
	v_cndmask_b32_e64 v41, v205, 0, vcc
	v_cndmask_b32_e64 v18, 1.0, 0, vcc
	v_cmp_eq_u32_e32 vcc, 0, v39
	v_add_u32_e32 v41, v40, v41
	global_load_dwordx4 v[162:165], v41, s[36:37]
	global_load_dwordx4 v[166:169], v41, s[36:37] offset:1024
	v_cndmask_b32_e64 v41, v206, 0, vcc
	v_cndmask_b32_e64 v20, 1.0, 0, vcc
	v_add_u32_e32 v41, v40, v41
	global_load_dwordx4 v[170:173], v41, s[36:37]
	global_load_dwordx4 v[174:177], v41, s[36:37] offset:1024
	global_load_dwordx4 v[178:181], v40, s[36:37]
	global_load_dwordx4 v[182:185], v40, s[36:37] offset:1024
	global_load_dwordx4 v[186:189], v40, s[36:37] offset:512
	global_load_dwordx4 v[190:193], v40, s[36:37] offset:1536
	s_waitcnt vmcnt(0)
	v_lshlrev_b32_e32 v22, 16, v44
	v_and_b32_e32 v23, 0xffff0000, v44
	v_lshlrev_b32_e32 v24, 16, v45
	v_and_b32_e32 v25, 0xffff0000, v45
	v_lshlrev_b32_e32 v26, 16, v46
	v_and_b32_e32 v27, 0xffff0000, v46
	v_lshlrev_b32_e32 v28, 16, v47
	v_and_b32_e32 v29, 0xffff0000, v47
	v_lshlrev_b32_e32 v30, 16, v48
	v_and_b32_e32 v31, 0xffff0000, v48
	v_lshlrev_b32_e32 v32, 16, v49
	v_and_b32_e32 v33, 0xffff0000, v49
	v_lshlrev_b32_e32 v34, 16, v50
	v_and_b32_e32 v35, 0xffff0000, v50
	v_lshlrev_b32_e32 v36, 16, v51
	v_and_b32_e32 v37, 0xffff0000, v51
	v_pk_mul_f32 v[22:23], v[22:23], v[30:31]
	v_pk_mul_f32 v[24:25], v[24:25], v[32:33]
	v_pk_mul_f32 v[26:27], v[26:27], v[34:35]
	v_pk_mul_f32 v[28:29], v[28:29], v[36:37]
	v_pk_mul_f32 v[244:245], v[212:213], v[6:7] op_sel_hi:[1,0]
	v_pk_mul_f32 v[246:247], v[214:215], v[6:7] op_sel_hi:[1,0]
	v_pk_mul_f32 v[248:249], v[216:217], v[6:7] op_sel_hi:[1,0]
	v_pk_mul_f32 v[4:5], v[218:219], v[6:7] op_sel_hi:[1,0]
	v_pk_fma_f32 v[140:141], v[244:245], v[22:23], 0 op_sel_hi:[1,1,0]
	v_pk_fma_f32 v[142:143], v[246:247], v[24:25], 0 op_sel_hi:[1,1,0]
	v_pk_fma_f32 v[144:145], v[248:249], v[26:27], 0 op_sel_hi:[1,1,0]
	v_pk_fma_f32 v[194:195], v[4:5], v[28:29], 0 op_sel_hi:[1,1,0]
	v_lshlrev_b32_e32 v22, 16, v52
	v_and_b32_e32 v23, 0xffff0000, v52
	v_lshlrev_b32_e32 v24, 16, v53
	v_and_b32_e32 v25, 0xffff0000, v53
	v_lshlrev_b32_e32 v26, 16, v54
	v_and_b32_e32 v27, 0xffff0000, v54
	v_lshlrev_b32_e32 v28, 16, v55
	v_and_b32_e32 v29, 0xffff0000, v55
	v_lshlrev_b32_e32 v30, 16, v56
	v_and_b32_e32 v31, 0xffff0000, v56
	v_lshlrev_b32_e32 v32, 16, v57
	v_and_b32_e32 v33, 0xffff0000, v57
	v_lshlrev_b32_e32 v34, 16, v58
	v_and_b32_e32 v35, 0xffff0000, v58
	v_lshlrev_b32_e32 v36, 16, v59
	v_and_b32_e32 v37, 0xffff0000, v59
	v_pk_mul_f32 v[22:23], v[22:23], v[30:31]
	v_pk_mul_f32 v[24:25], v[24:25], v[32:33]
	v_pk_mul_f32 v[26:27], v[26:27], v[34:35]
	v_pk_mul_f32 v[28:29], v[28:29], v[36:37]
	v_pk_mul_f32 v[244:245], v[220:221], v[8:9] op_sel_hi:[1,0]
	v_pk_mul_f32 v[246:247], v[222:223], v[8:9] op_sel_hi:[1,0]
	v_pk_mul_f32 v[248:249], v[224:225], v[8:9] op_sel_hi:[1,0]
	v_pk_mul_f32 v[4:5], v[226:227], v[8:9] op_sel_hi:[1,0]
	v_pk_fma_f32 v[140:141], v[244:245], v[22:23], v[140:141]
	v_pk_fma_f32 v[142:143], v[246:247], v[24:25], v[142:143]
	v_pk_fma_f32 v[144:145], v[248:249], v[26:27], v[144:145]
	v_pk_fma_f32 v[194:195], v[4:5], v[28:29], v[194:195]
	v_lshlrev_b32_e32 v22, 16, v60
	v_and_b32_e32 v23, 0xffff0000, v60
	v_lshlrev_b32_e32 v24, 16, v61
	v_and_b32_e32 v25, 0xffff0000, v61
	v_lshlrev_b32_e32 v26, 16, v62
	v_and_b32_e32 v27, 0xffff0000, v62
	v_lshlrev_b32_e32 v28, 16, v63
	v_and_b32_e32 v29, 0xffff0000, v63
	v_lshlrev_b32_e32 v30, 16, v64
	v_and_b32_e32 v31, 0xffff0000, v64
	v_lshlrev_b32_e32 v32, 16, v65
	v_and_b32_e32 v33, 0xffff0000, v65
	v_lshlrev_b32_e32 v34, 16, v66
	v_and_b32_e32 v35, 0xffff0000, v66
	v_lshlrev_b32_e32 v36, 16, v67
	v_and_b32_e32 v37, 0xffff0000, v67
	v_pk_mul_f32 v[22:23], v[22:23], v[30:31]
	v_pk_mul_f32 v[24:25], v[24:25], v[32:33]
	v_pk_mul_f32 v[26:27], v[26:27], v[34:35]
	v_pk_mul_f32 v[28:29], v[28:29], v[36:37]
	v_pk_fma_f32 v[140:141], v[228:229], v[22:23], v[140:141]
	v_pk_fma_f32 v[142:143], v[230:231], v[24:25], v[142:143]
	v_pk_fma_f32 v[144:145], v[232:233], v[26:27], v[144:145]
	v_pk_fma_f32 v[194:195], v[234:235], v[28:29], v[194:195]
	v_pk_add_f32 v[140:141], v[236:237], v[140:141]
	v_pk_add_f32 v[142:143], v[238:239], v[142:143]
	v_pk_add_f32 v[144:145], v[240:241], v[144:145]
	v_pk_add_f32 v[194:195], v[242:243], v[194:195]
	v_lshlrev_b32_e32 v30, 16, v68
	v_and_b32_e32 v31, 0xffff0000, v68
	v_lshlrev_b32_e32 v32, 16, v69
	v_and_b32_e32 v33, 0xffff0000, v69
	v_lshlrev_b32_e32 v34, 16, v70
	v_and_b32_e32 v35, 0xffff0000, v70
	v_lshlrev_b32_e32 v36, 16, v71
	v_and_b32_e32 v37, 0xffff0000, v71
	v_lshlrev_b32_e32 v22, 16, v72
	v_and_b32_e32 v23, 0xffff0000, v72
	v_lshlrev_b32_e32 v24, 16, v73
	v_and_b32_e32 v25, 0xffff0000, v73
	v_lshlrev_b32_e32 v26, 16, v74
	v_and_b32_e32 v27, 0xffff0000, v74
	v_lshlrev_b32_e32 v28, 16, v75
	v_and_b32_e32 v29, 0xffff0000, v75
	v_pk_mul_f32 v[140:141], v[140:141], v[30:31]
	v_pk_mul_f32 v[142:143], v[142:143], v[32:33]
	v_pk_mul_f32 v[144:145], v[144:145], v[34:35]
	v_pk_mul_f32 v[194:195], v[194:195], v[36:37]
	v_mul_f32_e32 v30, 0xbfb8aa3b, v22
	v_mul_f32_e32 v31, 0xbfb8aa3b, v23
	v_mul_f32_e32 v32, 0xbfb8aa3b, v24
	v_mul_f32_e32 v33, 0xbfb8aa3b, v25
	v_mul_f32_e32 v34, 0xbfb8aa3b, v26
	v_mul_f32_e32 v35, 0xbfb8aa3b, v27
	v_mul_f32_e32 v36, 0xbfb8aa3b, v28
	v_mul_f32_e32 v37, 0xbfb8aa3b, v29
	v_exp_f32_e32 v30, v30
	v_exp_f32_e32 v31, v31
	v_exp_f32_e32 v32, v32
	v_exp_f32_e32 v33, v33
	v_exp_f32_e32 v34, v34
	v_exp_f32_e32 v35, v35
	v_exp_f32_e32 v36, v36
	v_exp_f32_e32 v37, v37
	v_add_f32_e32 v30, 1.0, v30
	v_add_f32_e32 v31, 1.0, v31
	v_add_f32_e32 v32, 1.0, v32
	v_add_f32_e32 v33, 1.0, v33
	v_add_f32_e32 v34, 1.0, v34
	v_add_f32_e32 v35, 1.0, v35
	v_add_f32_e32 v36, 1.0, v36
	v_add_f32_e32 v37, 1.0, v37
	v_rcp_f32_e32 v30, v30
	v_rcp_f32_e32 v31, v31
	v_rcp_f32_e32 v32, v32
	v_rcp_f32_e32 v33, v33
	v_rcp_f32_e32 v34, v34
	v_rcp_f32_e32 v35, v35
	v_rcp_f32_e32 v36, v36
	v_rcp_f32_e32 v37, v37
	v_pk_mul_f32 v[30:31], v[30:31], v[22:23]
	v_pk_mul_f32 v[32:33], v[32:33], v[24:25]
	v_pk_mul_f32 v[34:35], v[34:35], v[26:27]
	v_pk_mul_f32 v[36:37], v[36:37], v[28:29]
	v_pk_mul_f32 v[140:141], v[140:141], v[30:31]
	v_pk_mul_f32 v[142:143], v[142:143], v[32:33]
	v_pk_mul_f32 v[144:145], v[144:145], v[34:35]
	v_pk_mul_f32 v[194:195], v[194:195], v[36:37]
	v_cvt_pk_bf16_f32 v44, v140, v141
	v_cvt_pk_bf16_f32 v45, v142, v143
	v_cvt_pk_bf16_f32 v46, v144, v145
	v_cvt_pk_bf16_f32 v47, v194, v195
	global_store_dwordx4 v42, v[44:47], s[34:35]
	v_lshlrev_b32_e32 v22, 16, v76
	v_and_b32_e32 v23, 0xffff0000, v76
	v_lshlrev_b32_e32 v24, 16, v77
	v_and_b32_e32 v25, 0xffff0000, v77
	v_lshlrev_b32_e32 v26, 16, v78
	v_and_b32_e32 v27, 0xffff0000, v78
	v_lshlrev_b32_e32 v28, 16, v79
	v_and_b32_e32 v29, 0xffff0000, v79
	v_lshlrev_b32_e32 v30, 16, v80
	v_and_b32_e32 v31, 0xffff0000, v80
	v_lshlrev_b32_e32 v32, 16, v81
	v_and_b32_e32 v33, 0xffff0000, v81
	v_lshlrev_b32_e32 v34, 16, v82
	v_and_b32_e32 v35, 0xffff0000, v82
	v_lshlrev_b32_e32 v36, 16, v83
	v_and_b32_e32 v37, 0xffff0000, v83
	v_pk_mul_f32 v[22:23], v[22:23], v[30:31]
	v_pk_mul_f32 v[24:25], v[24:25], v[32:33]
	v_pk_mul_f32 v[26:27], v[26:27], v[34:35]
	v_pk_mul_f32 v[28:29], v[28:29], v[36:37]
	v_pk_mul_f32 v[244:245], v[212:213], v[10:11] op_sel_hi:[1,0]
	v_pk_mul_f32 v[246:247], v[214:215], v[10:11] op_sel_hi:[1,0]
	v_pk_mul_f32 v[248:249], v[216:217], v[10:11] op_sel_hi:[1,0]
	v_pk_mul_f32 v[4:5], v[218:219], v[10:11] op_sel_hi:[1,0]
	v_pk_fma_f32 v[140:141], v[244:245], v[22:23], 0 op_sel_hi:[1,1,0]
	v_pk_fma_f32 v[142:143], v[246:247], v[24:25], 0 op_sel_hi:[1,1,0]
	v_pk_fma_f32 v[144:145], v[248:249], v[26:27], 0 op_sel_hi:[1,1,0]
	v_pk_fma_f32 v[194:195], v[4:5], v[28:29], 0 op_sel_hi:[1,1,0]
	v_lshlrev_b32_e32 v22, 16, v84
	v_and_b32_e32 v23, 0xffff0000, v84
	v_lshlrev_b32_e32 v24, 16, v85
	v_and_b32_e32 v25, 0xffff0000, v85
	v_lshlrev_b32_e32 v26, 16, v86
	v_and_b32_e32 v27, 0xffff0000, v86
	v_lshlrev_b32_e32 v28, 16, v87
	v_and_b32_e32 v29, 0xffff0000, v87
	v_lshlrev_b32_e32 v30, 16, v88
	v_and_b32_e32 v31, 0xffff0000, v88
	v_lshlrev_b32_e32 v32, 16, v89
	v_and_b32_e32 v33, 0xffff0000, v89
	v_lshlrev_b32_e32 v34, 16, v90
	v_and_b32_e32 v35, 0xffff0000, v90
	v_lshlrev_b32_e32 v36, 16, v91
	v_and_b32_e32 v37, 0xffff0000, v91
	v_pk_mul_f32 v[22:23], v[22:23], v[30:31]
	v_pk_mul_f32 v[24:25], v[24:25], v[32:33]
	v_pk_mul_f32 v[26:27], v[26:27], v[34:35]
	v_pk_mul_f32 v[28:29], v[28:29], v[36:37]
	v_pk_mul_f32 v[244:245], v[220:221], v[12:13] op_sel_hi:[1,0]
	v_pk_mul_f32 v[246:247], v[222:223], v[12:13] op_sel_hi:[1,0]
	v_pk_mul_f32 v[248:249], v[224:225], v[12:13] op_sel_hi:[1,0]
	v_pk_mul_f32 v[4:5], v[226:227], v[12:13] op_sel_hi:[1,0]
	v_pk_fma_f32 v[140:141], v[244:245], v[22:23], v[140:141]
	v_pk_fma_f32 v[142:143], v[246:247], v[24:25], v[142:143]
	v_pk_fma_f32 v[144:145], v[248:249], v[26:27], v[144:145]
	v_pk_fma_f32 v[194:195], v[4:5], v[28:29], v[194:195]
	v_lshlrev_b32_e32 v22, 16, v92
	v_and_b32_e32 v23, 0xffff0000, v92
	v_lshlrev_b32_e32 v24, 16, v93
	v_and_b32_e32 v25, 0xffff0000, v93
	v_lshlrev_b32_e32 v26, 16, v94
	v_and_b32_e32 v27, 0xffff0000, v94
	v_lshlrev_b32_e32 v28, 16, v95
	v_and_b32_e32 v29, 0xffff0000, v95
	v_lshlrev_b32_e32 v30, 16, v96
	v_and_b32_e32 v31, 0xffff0000, v96
	v_lshlrev_b32_e32 v32, 16, v97
	v_and_b32_e32 v33, 0xffff0000, v97
	v_lshlrev_b32_e32 v34, 16, v98
	v_and_b32_e32 v35, 0xffff0000, v98
	v_lshlrev_b32_e32 v36, 16, v99
	v_and_b32_e32 v37, 0xffff0000, v99
	v_pk_mul_f32 v[22:23], v[22:23], v[30:31]
	v_pk_mul_f32 v[24:25], v[24:25], v[32:33]
	v_pk_mul_f32 v[26:27], v[26:27], v[34:35]
	v_pk_mul_f32 v[28:29], v[28:29], v[36:37]
	v_pk_fma_f32 v[140:141], v[228:229], v[22:23], v[140:141]
	v_pk_fma_f32 v[142:143], v[230:231], v[24:25], v[142:143]
	v_pk_fma_f32 v[144:145], v[232:233], v[26:27], v[144:145]
	v_pk_fma_f32 v[194:195], v[234:235], v[28:29], v[194:195]
	v_pk_add_f32 v[140:141], v[236:237], v[140:141]
	v_pk_add_f32 v[142:143], v[238:239], v[142:143]
	v_pk_add_f32 v[144:145], v[240:241], v[144:145]
	v_pk_add_f32 v[194:195], v[242:243], v[194:195]
	v_lshlrev_b32_e32 v30, 16, v100
	v_and_b32_e32 v31, 0xffff0000, v100
	v_lshlrev_b32_e32 v32, 16, v101
	v_and_b32_e32 v33, 0xffff0000, v101
	v_lshlrev_b32_e32 v34, 16, v102
	v_and_b32_e32 v35, 0xffff0000, v102
	v_lshlrev_b32_e32 v36, 16, v103
	v_and_b32_e32 v37, 0xffff0000, v103
	v_lshlrev_b32_e32 v22, 16, v104
	v_and_b32_e32 v23, 0xffff0000, v104
	v_lshlrev_b32_e32 v24, 16, v105
	v_and_b32_e32 v25, 0xffff0000, v105
	v_lshlrev_b32_e32 v26, 16, v106
	v_and_b32_e32 v27, 0xffff0000, v106
	v_lshlrev_b32_e32 v28, 16, v107
	v_and_b32_e32 v29, 0xffff0000, v107
	v_pk_mul_f32 v[140:141], v[140:141], v[30:31]
	v_pk_mul_f32 v[142:143], v[142:143], v[32:33]
	v_pk_mul_f32 v[144:145], v[144:145], v[34:35]
	v_pk_mul_f32 v[194:195], v[194:195], v[36:37]
	v_mul_f32_e32 v30, 0xbfb8aa3b, v22
	v_mul_f32_e32 v31, 0xbfb8aa3b, v23
	v_mul_f32_e32 v32, 0xbfb8aa3b, v24
	v_mul_f32_e32 v33, 0xbfb8aa3b, v25
	v_mul_f32_e32 v34, 0xbfb8aa3b, v26
	v_mul_f32_e32 v35, 0xbfb8aa3b, v27
	v_mul_f32_e32 v36, 0xbfb8aa3b, v28
	v_mul_f32_e32 v37, 0xbfb8aa3b, v29
	v_exp_f32_e32 v30, v30
	v_exp_f32_e32 v31, v31
	v_exp_f32_e32 v32, v32
	v_exp_f32_e32 v33, v33
	v_exp_f32_e32 v34, v34
	v_exp_f32_e32 v35, v35
	v_exp_f32_e32 v36, v36
	v_exp_f32_e32 v37, v37
	v_add_f32_e32 v30, 1.0, v30
	v_add_f32_e32 v31, 1.0, v31
	v_add_f32_e32 v32, 1.0, v32
	v_add_f32_e32 v33, 1.0, v33
	v_add_f32_e32 v34, 1.0, v34
	v_add_f32_e32 v35, 1.0, v35
	v_add_f32_e32 v36, 1.0, v36
	v_add_f32_e32 v37, 1.0, v37
	v_rcp_f32_e32 v30, v30
	v_rcp_f32_e32 v31, v31
	v_rcp_f32_e32 v32, v32
	v_rcp_f32_e32 v33, v33
	v_rcp_f32_e32 v34, v34
	v_rcp_f32_e32 v35, v35
	v_rcp_f32_e32 v36, v36
	v_rcp_f32_e32 v37, v37
	v_pk_mul_f32 v[30:31], v[30:31], v[22:23]
	v_pk_mul_f32 v[32:33], v[32:33], v[24:25]
	v_pk_mul_f32 v[34:35], v[34:35], v[26:27]
	v_pk_mul_f32 v[36:37], v[36:37], v[28:29]
	v_pk_mul_f32 v[140:141], v[140:141], v[30:31]
	v_pk_mul_f32 v[142:143], v[142:143], v[32:33]
	v_pk_mul_f32 v[144:145], v[144:145], v[34:35]
	v_pk_mul_f32 v[194:195], v[194:195], v[36:37]
	v_cvt_pk_bf16_f32 v76, v140, v141
	v_cvt_pk_bf16_f32 v77, v142, v143
	v_cvt_pk_bf16_f32 v78, v144, v145
	v_cvt_pk_bf16_f32 v79, v194, v195
	global_store_dwordx4 v9, v[76:79], s[34:35]
	v_lshlrev_b32_e32 v22, 16, v108
	v_and_b32_e32 v23, 0xffff0000, v108
	v_lshlrev_b32_e32 v24, 16, v109
	v_and_b32_e32 v25, 0xffff0000, v109
	v_lshlrev_b32_e32 v26, 16, v110
	v_and_b32_e32 v27, 0xffff0000, v110
	v_lshlrev_b32_e32 v28, 16, v111
	v_and_b32_e32 v29, 0xffff0000, v111
	v_lshlrev_b32_e32 v30, 16, v112
	v_and_b32_e32 v31, 0xffff0000, v112
	v_lshlrev_b32_e32 v32, 16, v113
	v_and_b32_e32 v33, 0xffff0000, v113
	v_lshlrev_b32_e32 v34, 16, v114
	v_and_b32_e32 v35, 0xffff0000, v114
	v_lshlrev_b32_e32 v36, 16, v115
	v_and_b32_e32 v37, 0xffff0000, v115
	v_pk_mul_f32 v[22:23], v[22:23], v[30:31]
	v_pk_mul_f32 v[24:25], v[24:25], v[32:33]
	v_pk_mul_f32 v[26:27], v[26:27], v[34:35]
	v_pk_mul_f32 v[28:29], v[28:29], v[36:37]
	v_pk_mul_f32 v[244:245], v[212:213], v[14:15] op_sel_hi:[1,0]
	v_pk_mul_f32 v[246:247], v[214:215], v[14:15] op_sel_hi:[1,0]
	v_pk_mul_f32 v[248:249], v[216:217], v[14:15] op_sel_hi:[1,0]
	v_pk_mul_f32 v[4:5], v[218:219], v[14:15] op_sel_hi:[1,0]
	v_pk_fma_f32 v[140:141], v[244:245], v[22:23], 0 op_sel_hi:[1,1,0]
	v_pk_fma_f32 v[142:143], v[246:247], v[24:25], 0 op_sel_hi:[1,1,0]
	v_pk_fma_f32 v[144:145], v[248:249], v[26:27], 0 op_sel_hi:[1,1,0]
	v_pk_fma_f32 v[194:195], v[4:5], v[28:29], 0 op_sel_hi:[1,1,0]
	v_lshlrev_b32_e32 v22, 16, v116
	v_and_b32_e32 v23, 0xffff0000, v116
	v_lshlrev_b32_e32 v24, 16, v117
	v_and_b32_e32 v25, 0xffff0000, v117
	v_lshlrev_b32_e32 v26, 16, v118
	v_and_b32_e32 v27, 0xffff0000, v118
	v_lshlrev_b32_e32 v28, 16, v119
	v_and_b32_e32 v29, 0xffff0000, v119
	v_lshlrev_b32_e32 v30, 16, v120
	v_and_b32_e32 v31, 0xffff0000, v120
	v_lshlrev_b32_e32 v32, 16, v121
	v_and_b32_e32 v33, 0xffff0000, v121
	v_lshlrev_b32_e32 v34, 16, v122
	v_and_b32_e32 v35, 0xffff0000, v122
	v_lshlrev_b32_e32 v36, 16, v123
	v_and_b32_e32 v37, 0xffff0000, v123
	v_pk_mul_f32 v[22:23], v[22:23], v[30:31]
	v_pk_mul_f32 v[24:25], v[24:25], v[32:33]
	v_pk_mul_f32 v[26:27], v[26:27], v[34:35]
	v_pk_mul_f32 v[28:29], v[28:29], v[36:37]
	v_pk_mul_f32 v[244:245], v[220:221], v[16:17] op_sel_hi:[1,0]
	v_pk_mul_f32 v[246:247], v[222:223], v[16:17] op_sel_hi:[1,0]
	v_pk_mul_f32 v[248:249], v[224:225], v[16:17] op_sel_hi:[1,0]
	v_pk_mul_f32 v[4:5], v[226:227], v[16:17] op_sel_hi:[1,0]
	v_pk_fma_f32 v[140:141], v[244:245], v[22:23], v[140:141]
	v_pk_fma_f32 v[142:143], v[246:247], v[24:25], v[142:143]
	v_pk_fma_f32 v[144:145], v[248:249], v[26:27], v[144:145]
	v_pk_fma_f32 v[194:195], v[4:5], v[28:29], v[194:195]
	v_lshlrev_b32_e32 v22, 16, v124
	v_and_b32_e32 v23, 0xffff0000, v124
	v_lshlrev_b32_e32 v24, 16, v125
	v_and_b32_e32 v25, 0xffff0000, v125
	v_lshlrev_b32_e32 v26, 16, v126
	v_and_b32_e32 v27, 0xffff0000, v126
	v_lshlrev_b32_e32 v28, 16, v127
	v_and_b32_e32 v29, 0xffff0000, v127
	v_lshlrev_b32_e32 v30, 16, v128
	v_and_b32_e32 v31, 0xffff0000, v128
	v_lshlrev_b32_e32 v32, 16, v129
	v_and_b32_e32 v33, 0xffff0000, v129
	v_lshlrev_b32_e32 v34, 16, v130
	v_and_b32_e32 v35, 0xffff0000, v130
	v_lshlrev_b32_e32 v36, 16, v131
	v_and_b32_e32 v37, 0xffff0000, v131
	v_pk_mul_f32 v[22:23], v[22:23], v[30:31]
	v_pk_mul_f32 v[24:25], v[24:25], v[32:33]
	v_pk_mul_f32 v[26:27], v[26:27], v[34:35]
	v_pk_mul_f32 v[28:29], v[28:29], v[36:37]
	v_pk_fma_f32 v[140:141], v[228:229], v[22:23], v[140:141]
	v_pk_fma_f32 v[142:143], v[230:231], v[24:25], v[142:143]
	v_pk_fma_f32 v[144:145], v[232:233], v[26:27], v[144:145]
	v_pk_fma_f32 v[194:195], v[234:235], v[28:29], v[194:195]
	v_pk_add_f32 v[140:141], v[236:237], v[140:141]
	v_pk_add_f32 v[142:143], v[238:239], v[142:143]
	v_pk_add_f32 v[144:145], v[240:241], v[144:145]
	v_pk_add_f32 v[194:195], v[242:243], v[194:195]
	v_lshlrev_b32_e32 v30, 16, v132
	v_and_b32_e32 v31, 0xffff0000, v132
	v_lshlrev_b32_e32 v32, 16, v133
	v_and_b32_e32 v33, 0xffff0000, v133
	v_lshlrev_b32_e32 v34, 16, v134
	v_and_b32_e32 v35, 0xffff0000, v134
	v_lshlrev_b32_e32 v36, 16, v135
	v_and_b32_e32 v37, 0xffff0000, v135
	v_lshlrev_b32_e32 v22, 16, v136
	v_and_b32_e32 v23, 0xffff0000, v136
	v_lshlrev_b32_e32 v24, 16, v137
	v_and_b32_e32 v25, 0xffff0000, v137
	v_lshlrev_b32_e32 v26, 16, v138
	v_and_b32_e32 v27, 0xffff0000, v138
	v_lshlrev_b32_e32 v28, 16, v139
	v_and_b32_e32 v29, 0xffff0000, v139
	v_pk_mul_f32 v[140:141], v[140:141], v[30:31]
	v_pk_mul_f32 v[142:143], v[142:143], v[32:33]
	v_pk_mul_f32 v[144:145], v[144:145], v[34:35]
	v_pk_mul_f32 v[194:195], v[194:195], v[36:37]
	v_mul_f32_e32 v30, 0xbfb8aa3b, v22
	v_mul_f32_e32 v31, 0xbfb8aa3b, v23
	v_mul_f32_e32 v32, 0xbfb8aa3b, v24
	v_mul_f32_e32 v33, 0xbfb8aa3b, v25
	v_mul_f32_e32 v34, 0xbfb8aa3b, v26
	v_mul_f32_e32 v35, 0xbfb8aa3b, v27
	v_mul_f32_e32 v36, 0xbfb8aa3b, v28
	v_mul_f32_e32 v37, 0xbfb8aa3b, v29
	v_exp_f32_e32 v30, v30
	v_exp_f32_e32 v31, v31
	v_exp_f32_e32 v32, v32
	v_exp_f32_e32 v33, v33
	v_exp_f32_e32 v34, v34
	v_exp_f32_e32 v35, v35
	v_exp_f32_e32 v36, v36
	v_exp_f32_e32 v37, v37
	v_add_f32_e32 v30, 1.0, v30
	v_add_f32_e32 v31, 1.0, v31
	v_add_f32_e32 v32, 1.0, v32
	v_add_f32_e32 v33, 1.0, v33
	v_add_f32_e32 v34, 1.0, v34
	v_add_f32_e32 v35, 1.0, v35
	v_add_f32_e32 v36, 1.0, v36
	v_add_f32_e32 v37, 1.0, v37
	v_rcp_f32_e32 v30, v30
	v_rcp_f32_e32 v31, v31
	v_rcp_f32_e32 v32, v32
	v_rcp_f32_e32 v33, v33
	v_rcp_f32_e32 v34, v34
	v_rcp_f32_e32 v35, v35
	v_rcp_f32_e32 v36, v36
	v_rcp_f32_e32 v37, v37
	v_pk_mul_f32 v[30:31], v[30:31], v[22:23]
	v_pk_mul_f32 v[32:33], v[32:33], v[24:25]
	v_pk_mul_f32 v[34:35], v[34:35], v[26:27]
	v_pk_mul_f32 v[36:37], v[36:37], v[28:29]
	v_pk_mul_f32 v[140:141], v[140:141], v[30:31]
	v_pk_mul_f32 v[142:143], v[142:143], v[32:33]
	v_pk_mul_f32 v[144:145], v[144:145], v[34:35]
	v_pk_mul_f32 v[194:195], v[194:195], v[36:37]
	v_cvt_pk_bf16_f32 v108, v140, v141
	v_cvt_pk_bf16_f32 v109, v142, v143
	v_cvt_pk_bf16_f32 v110, v144, v145
	v_cvt_pk_bf16_f32 v111, v194, v195
	global_store_dwordx4 v13, v[108:111], s[34:35]
	v_lshlrev_b32_e32 v22, 16, v162
	v_and_b32_e32 v23, 0xffff0000, v162
	v_lshlrev_b32_e32 v24, 16, v163
	v_and_b32_e32 v25, 0xffff0000, v163
	v_lshlrev_b32_e32 v26, 16, v164
	v_and_b32_e32 v27, 0xffff0000, v164
	v_lshlrev_b32_e32 v28, 16, v165
	v_and_b32_e32 v29, 0xffff0000, v165
	v_lshlrev_b32_e32 v30, 16, v166
	v_and_b32_e32 v31, 0xffff0000, v166
	v_lshlrev_b32_e32 v32, 16, v167
	v_and_b32_e32 v33, 0xffff0000, v167
	v_lshlrev_b32_e32 v34, 16, v168
	v_and_b32_e32 v35, 0xffff0000, v168
	v_lshlrev_b32_e32 v36, 16, v169
	v_and_b32_e32 v37, 0xffff0000, v169
	v_pk_mul_f32 v[22:23], v[22:23], v[30:31]
	v_pk_mul_f32 v[24:25], v[24:25], v[32:33]
	v_pk_mul_f32 v[26:27], v[26:27], v[34:35]
	v_pk_mul_f32 v[28:29], v[28:29], v[36:37]
	v_pk_mul_f32 v[244:245], v[212:213], v[18:19] op_sel_hi:[1,0]
	v_pk_mul_f32 v[246:247], v[214:215], v[18:19] op_sel_hi:[1,0]
	v_pk_mul_f32 v[248:249], v[216:217], v[18:19] op_sel_hi:[1,0]
	v_pk_mul_f32 v[4:5], v[218:219], v[18:19] op_sel_hi:[1,0]
	v_pk_fma_f32 v[140:141], v[244:245], v[22:23], 0 op_sel_hi:[1,1,0]
	v_pk_fma_f32 v[142:143], v[246:247], v[24:25], 0 op_sel_hi:[1,1,0]
	v_pk_fma_f32 v[144:145], v[248:249], v[26:27], 0 op_sel_hi:[1,1,0]
	v_pk_fma_f32 v[194:195], v[4:5], v[28:29], 0 op_sel_hi:[1,1,0]
	v_lshlrev_b32_e32 v22, 16, v170
	v_and_b32_e32 v23, 0xffff0000, v170
	v_lshlrev_b32_e32 v24, 16, v171
	v_and_b32_e32 v25, 0xffff0000, v171
	v_lshlrev_b32_e32 v26, 16, v172
	v_and_b32_e32 v27, 0xffff0000, v172
	v_lshlrev_b32_e32 v28, 16, v173
	v_and_b32_e32 v29, 0xffff0000, v173
	v_lshlrev_b32_e32 v30, 16, v174
	v_and_b32_e32 v31, 0xffff0000, v174
	v_lshlrev_b32_e32 v32, 16, v175
	v_and_b32_e32 v33, 0xffff0000, v175
	v_lshlrev_b32_e32 v34, 16, v176
	v_and_b32_e32 v35, 0xffff0000, v176
	v_lshlrev_b32_e32 v36, 16, v177
	v_and_b32_e32 v37, 0xffff0000, v177
	v_pk_mul_f32 v[22:23], v[22:23], v[30:31]
	v_pk_mul_f32 v[24:25], v[24:25], v[32:33]
	v_pk_mul_f32 v[26:27], v[26:27], v[34:35]
	v_pk_mul_f32 v[28:29], v[28:29], v[36:37]
	v_pk_mul_f32 v[244:245], v[220:221], v[20:21] op_sel_hi:[1,0]
	v_pk_mul_f32 v[246:247], v[222:223], v[20:21] op_sel_hi:[1,0]
	v_pk_mul_f32 v[248:249], v[224:225], v[20:21] op_sel_hi:[1,0]
	v_pk_mul_f32 v[4:5], v[226:227], v[20:21] op_sel_hi:[1,0]
	v_pk_fma_f32 v[140:141], v[244:245], v[22:23], v[140:141]
	v_pk_fma_f32 v[142:143], v[246:247], v[24:25], v[142:143]
	v_pk_fma_f32 v[144:145], v[248:249], v[26:27], v[144:145]
	v_pk_fma_f32 v[194:195], v[4:5], v[28:29], v[194:195]
	v_lshlrev_b32_e32 v22, 16, v178
	v_and_b32_e32 v23, 0xffff0000, v178
	v_lshlrev_b32_e32 v24, 16, v179
	v_and_b32_e32 v25, 0xffff0000, v179
	v_lshlrev_b32_e32 v26, 16, v180
	v_and_b32_e32 v27, 0xffff0000, v180
	v_lshlrev_b32_e32 v28, 16, v181
	v_and_b32_e32 v29, 0xffff0000, v181
	v_lshlrev_b32_e32 v30, 16, v182
	v_and_b32_e32 v31, 0xffff0000, v182
	v_lshlrev_b32_e32 v32, 16, v183
	v_and_b32_e32 v33, 0xffff0000, v183
	v_lshlrev_b32_e32 v34, 16, v184
	v_and_b32_e32 v35, 0xffff0000, v184
	v_lshlrev_b32_e32 v36, 16, v185
	v_and_b32_e32 v37, 0xffff0000, v185
	v_pk_mul_f32 v[22:23], v[22:23], v[30:31]
	v_pk_mul_f32 v[24:25], v[24:25], v[32:33]
	v_pk_mul_f32 v[26:27], v[26:27], v[34:35]
	v_pk_mul_f32 v[28:29], v[28:29], v[36:37]
	v_pk_fma_f32 v[140:141], v[228:229], v[22:23], v[140:141]
	v_pk_fma_f32 v[142:143], v[230:231], v[24:25], v[142:143]
	v_pk_fma_f32 v[144:145], v[232:233], v[26:27], v[144:145]
	v_pk_fma_f32 v[194:195], v[234:235], v[28:29], v[194:195]
	v_pk_add_f32 v[140:141], v[236:237], v[140:141]
	v_pk_add_f32 v[142:143], v[238:239], v[142:143]
	v_pk_add_f32 v[144:145], v[240:241], v[144:145]
	v_pk_add_f32 v[194:195], v[242:243], v[194:195]
	v_lshlrev_b32_e32 v30, 16, v186
	v_and_b32_e32 v31, 0xffff0000, v186
	v_lshlrev_b32_e32 v32, 16, v187
	v_and_b32_e32 v33, 0xffff0000, v187
	v_lshlrev_b32_e32 v34, 16, v188
	v_and_b32_e32 v35, 0xffff0000, v188
	v_lshlrev_b32_e32 v36, 16, v189
	v_and_b32_e32 v37, 0xffff0000, v189
	v_lshlrev_b32_e32 v22, 16, v190
	v_and_b32_e32 v23, 0xffff0000, v190
	v_lshlrev_b32_e32 v24, 16, v191
	v_and_b32_e32 v25, 0xffff0000, v191
	v_lshlrev_b32_e32 v26, 16, v192
	v_and_b32_e32 v27, 0xffff0000, v192
	v_lshlrev_b32_e32 v28, 16, v193
	v_and_b32_e32 v29, 0xffff0000, v193
	v_pk_mul_f32 v[140:141], v[140:141], v[30:31]
	v_pk_mul_f32 v[142:143], v[142:143], v[32:33]
	v_pk_mul_f32 v[144:145], v[144:145], v[34:35]
	v_pk_mul_f32 v[194:195], v[194:195], v[36:37]
	v_mul_f32_e32 v30, 0xbfb8aa3b, v22
	v_mul_f32_e32 v31, 0xbfb8aa3b, v23
	v_mul_f32_e32 v32, 0xbfb8aa3b, v24
	v_mul_f32_e32 v33, 0xbfb8aa3b, v25
	v_mul_f32_e32 v34, 0xbfb8aa3b, v26
	v_mul_f32_e32 v35, 0xbfb8aa3b, v27
	v_mul_f32_e32 v36, 0xbfb8aa3b, v28
	v_mul_f32_e32 v37, 0xbfb8aa3b, v29
	v_exp_f32_e32 v30, v30
	v_exp_f32_e32 v31, v31
	v_exp_f32_e32 v32, v32
	v_exp_f32_e32 v33, v33
	v_exp_f32_e32 v34, v34
	v_exp_f32_e32 v35, v35
	v_exp_f32_e32 v36, v36
	v_exp_f32_e32 v37, v37
	v_add_f32_e32 v30, 1.0, v30
	v_add_f32_e32 v31, 1.0, v31
	v_add_f32_e32 v32, 1.0, v32
	v_add_f32_e32 v33, 1.0, v33
	v_add_f32_e32 v34, 1.0, v34
	v_add_f32_e32 v35, 1.0, v35
	v_add_f32_e32 v36, 1.0, v36
	v_add_f32_e32 v37, 1.0, v37
	v_rcp_f32_e32 v30, v30
	v_rcp_f32_e32 v31, v31
	v_rcp_f32_e32 v32, v32
	v_rcp_f32_e32 v33, v33
	v_rcp_f32_e32 v34, v34
	v_rcp_f32_e32 v35, v35
	v_rcp_f32_e32 v36, v36
	v_rcp_f32_e32 v37, v37
	v_pk_mul_f32 v[30:31], v[30:31], v[22:23]
	v_pk_mul_f32 v[32:33], v[32:33], v[24:25]
	v_pk_mul_f32 v[34:35], v[34:35], v[26:27]
	v_pk_mul_f32 v[36:37], v[36:37], v[28:29]
	v_pk_mul_f32 v[140:141], v[140:141], v[30:31]
	v_pk_mul_f32 v[142:143], v[142:143], v[32:33]
	v_pk_mul_f32 v[144:145], v[144:145], v[34:35]
	v_pk_mul_f32 v[194:195], v[194:195], v[36:37]
	v_cvt_pk_bf16_f32 v162, v140, v141
	v_cvt_pk_bf16_f32 v163, v142, v143
	v_cvt_pk_bf16_f32 v164, v144, v145
	v_cvt_pk_bf16_f32 v165, v194, v195
	global_store_dwordx4 v17, v[162:165], s[34:35]
	s_mov_b64 s[2:3], exec
